# X30: attention pass B unit epilogue - the four norm-weight loads issued up front into free registers, one wait, four stores without intermediate waits
# baseline (speedup 1.0000x reference)
; __device__ __forceinline__ unsigned pkbf(float a, float b) { return pk2(a, b); }
; template <int KIND> __device__ __forceinline__ void attn_pass(const Args& a, unsigned char* ws, int l, int vcu, int G, LAS unsigned char* lds, int tid) {
;     ...
;             { float s = 0.f;
; #pragma unroll
;               for (int w = 0; w < 8; ++w) s += ssq[w * 16 + fr];
;               const float rs = 1.0f / sqrtf(s * (1.0f / 512.0f) + NORM_EPS); const float* nw = a.in[I_ATN] + l * 512 + head * 64;
; #pragma unroll
;               for (int dt = 0; dt < 4; ++dt) { const int dd = 16 * dt + 4 * g;
;                   *(v2u*)(Y + qrow * DM + 512 + head * 64 + dd) = (v2u){pkbf(o[dt][0] * rs * nw[dd], o[dt][1] * rs * nw[dd + 1]), pkbf(o[dt][2] * rs * nw[dd + 2], o[dt][3] * rs * nw[dd + 3])}; } }
.LBB0_1068:
	s_or_b64 exec, exec, s[44:45]
	global_load_dwordx4 v[240:243], v[152:153], off
	global_load_dwordx4 v[244:247], v[152:153], off offset:64
	global_load_dwordx4 v[248:251], v[152:153], off offset:128
	global_load_dwordx4 v[164:167], v[152:153], off offset:192
	v_add_u32_e32 v4, s66, v216
	s_waitcnt lgkmcnt(0)
	v_lshl_add_u64 v[92:93], v[4:5], 0, s[36:37]
	v_add_u32_e32 v4, 0x9000, v223
	s_barrier
	ds_read2_b32 v[96:97], v4 offset1:16
	v_lshlrev_b64 v[92:93], 12, v[92:93]
	v_lshl_add_u64 v[92:93], s[0:1], 0, v[92:93]
	v_lshl_add_u64 v[92:93], v[2:3], 1, v[92:93]
	v_mov_b32_e32 v157, v5
	s_waitcnt lgkmcnt(0)
	v_add_f32_e32 v96, 0, v96
	v_add_f32_e32 v98, v96, v97
	ds_read2_b32 v[96:97], v4 offset0:32 offset1:48
	s_mov_b32 s3, 0x2aa00000
	s_waitcnt lgkmcnt(0)
	v_add_f32_e32 v96, v98, v96
	v_add_f32_e32 v98, v96, v97
	ds_read2_b32 v[96:97], v4 offset0:64 offset1:80
	s_waitcnt lgkmcnt(0)
	v_add_f32_e32 v96, v98, v96
	v_add_f32_e32 v98, v96, v97
	ds_read2_b32 v[96:97], v4 offset0:96 offset1:112
	s_waitcnt lgkmcnt(0)
	v_add_f32_e32 v4, v98, v96
	v_add_f32_e32 v4, v4, v97
	v_fmamk_f32 v4, v4, 0x3b000000, v194
	v_cmp_gt_f32_e32 vcc, s79, v4
	v_mul_f32_e32 v96, 0x4f800000, v4
	s_nop 0
	v_cndmask_b32_e32 v4, v4, v96, vcc
	v_sqrt_f32_e32 v96, v4
	s_nop 0
	v_add_u32_e32 v97, -1, v96
	v_fma_f32 v98, -v97, v96, v4
	v_cmp_ge_f32_e64 s[44:45], 0, v98
	v_add_u32_e32 v98, 1, v96
	s_nop 0
	v_cndmask_b32_e64 v97, v96, v97, s[44:45]
	v_fma_f32 v96, -v98, v96, v4
	v_cmp_lt_f32_e64 s[44:45], 0, v96
	s_nop 1
	v_cndmask_b32_e64 v96, v97, v98, s[44:45]
	v_mul_f32_e32 v97, 0x37800000, v96
	v_cndmask_b32_e32 v96, v96, v97, vcc
	v_cmp_class_f32_e32 vcc, v4, v198
	s_nop 1
	v_cndmask_b32_e32 v4, v96, v4, vcc
	v_div_scale_f32 v96, s[34:35], v4, v4, 1.0
	v_rcp_f32_e32 v97, v96
	s_mov_b64 s[34:35], 0x2aa00400
	v_fma_f32 v98, -v96, v97, 1.0
	v_fmac_f32_e32 v97, v98, v97
	v_div_scale_f32 v98, vcc, 1.0, v4, 1.0
	v_mul_f32_e32 v99, v98, v97
	v_fma_f32 v100, -v96, v99, v98
	v_fmac_f32_e32 v99, v100, v97
	v_fma_f32 v96, -v96, v99, v98
	v_div_fmas_f32 v96, v96, v97, v99
	v_div_fixup_f32 v4, v96, v4, 1.0
	v_pk_mul_f32 v[98:99], v[94:95], v[4:5] op_sel_hi:[1,0]
	v_pk_mul_f32 v[90:91], v[90:91], v[4:5] op_sel_hi:[1,0]
	v_pk_mul_f32 v[84:85], v[84:85], v[4:5] op_sel_hi:[1,0]
	v_pk_mul_f32 v[78:79], v[78:79], v[4:5] op_sel_hi:[1,0]
	v_pk_mul_f32 v[80:81], v[80:81], v[4:5] op_sel_hi:[1,0]
	v_pk_mul_f32 v[88:89], v[88:89], v[4:5] op_sel_hi:[1,0]
	v_pk_mul_f32 v[86:87], v[86:87], v[4:5] op_sel_hi:[1,0]
	v_pk_mul_f32 v[82:83], v[82:83], v[4:5] op_sel_hi:[1,0]
	s_waitcnt vmcnt(0)
	v_pk_mul_f32 v[94:95], v[240:241], v[98:99]
	v_pk_mul_f32 v[90:91], v[242:243], v[90:91]
	v_cvt_pk_bf16_f32 v94, v94, v95
	v_cvt_pk_bf16_f32 v95, v90, v91
	v_lshl_add_u64 v[90:91], v[92:93], 0, v[156:157]
	v_lshl_add_u64 v[92:93], v[90:91], 0, s[34:35]
	v_add_co_u32_e32 v90, vcc, s3, v90
	s_nop 1
	v_addc_co_u32_e32 v91, vcc, 0, v91, vcc
	global_store_dwordx2 v[90:91], v[94:95], off offset:1024
	s_andn2_b64 vcc, exec, s[60:61]
	v_pk_mul_f32 v[88:89], v[88:89], v[244:245]
	v_pk_mul_f32 v[84:85], v[84:85], v[246:247]
	v_cvt_pk_bf16_f32 v88, v88, v89
	v_cvt_pk_bf16_f32 v89, v84, v85
	global_store_dwordx2 v[92:93], v[88:89], off offset:32
	v_pk_mul_f32 v[86:87], v[86:87], v[248:249]
	v_pk_mul_f32 v[78:79], v[78:79], v[250:251]
	v_cvt_pk_bf16_f32 v86, v86, v87
	v_cvt_pk_bf16_f32 v87, v78, v79
	global_store_dwordx2 v[92:93], v[86:87], off offset:64
	v_pk_mul_f32 v[82:83], v[82:83], v[164:165]
	v_pk_mul_f32 v[80:81], v[80:81], v[166:167]
	v_cvt_pk_bf16_f32 v82, v82, v83
	v_cvt_pk_bf16_f32 v83, v80, v81
	global_store_dwordx2 v[92:93], v[82:83], off offset:96
	v_mov_b64_e32 v[164:165], 0x400
	v_mov_b64_e32 v[166:167], 0x3ff
	s_cbranch_vccz .LBB0_1088
